# grid barrier: L1 invalidate issued by wave 1 at arrival, in parallel with thread 0's arrive/release protocol
# speedup vs baseline: 1.0066x; 1.0066x over previous
.LBB0_552:
	v_readlane_b32 s2, v216, 16
	v_readlane_b32 s3, v216, 17
	s_and_b64 vcc, exec, s[2:3]
	s_cbranch_vccz .LBB0_606
	s_waitcnt vmcnt(0)
	s_waitcnt vmcnt(0) lgkmcnt(0)
	s_barrier
	s_mov_b64 s[0:1], exec
	v_readfirstlane_b32 s2, v142
	s_lshr_b32 s2, s2, 6
	s_cmp_lg_u32 s2, 1
	s_cbranch_scc1 .Lbar_noinv
	buffer_inv sc1
	s_waitcnt vmcnt(0)
.Lbar_noinv:
	v_readlane_b32 s2, v217, 3
	v_readlane_b32 s3, v217, 4
	s_and_b64 s[2:3], s[0:1], s[2:3]
	s_mov_b64 exec, s[2:3]
	s_cbranch_execz .LBB0_605
	v_readlane_b32 s2, v214, 36
	s_waitcnt vmcnt(0) expcnt(0) lgkmcnt(0)
	s_nop 0
	v_mov_b32_e32 v0, s2
	ds_read_b32 v3, v0
	v_readlane_b32 s2, v214, 37
	s_waitcnt lgkmcnt(0)
	v_cmp_ne_u32_e32 vcc, 0, v3
	v_mov_b32_e32 v0, s2
	ds_read_b32 v2, v0
	s_cbranch_vccnz .LBB0_569
	s_mov_b32 s8, 1
	s_branch .LBB0_557

.LBB0_588:
	s_or_b64 exec, exec, s[4:5]
	s_waitcnt vmcnt(0)
	v_readfirstlane_b32 s2, v3
	v_sub_u32_e32 v4, 0, v2
	s_mov_b64 s[4:5], -1
	v_add_u32_e32 v3, s2, v0
	v_cvt_f32_u32_e32 v0, v2
	v_readlane_b32 s2, v215, 26
	v_readlane_b32 s3, v215, 27
	v_rcp_iflag_f32_e32 v0, v0
	s_nop 0
	v_mul_f32_e32 v0, 0x4f7ffffe, v0
	v_cvt_u32_f32_e32 v0, v0
	v_mul_lo_u32 v4, v4, v0
	v_mul_hi_u32 v4, v0, v4
	v_add_u32_e32 v0, v0, v4
	v_mul_hi_u32 v0, v3, v0
	v_mul_lo_u32 v4, v0, v2
	v_sub_u32_e32 v4, v3, v4
	v_cmp_ge_u32_e32 vcc, v4, v2
	v_add_u32_e32 v5, 1, v0
	v_add_u32_e32 v3, 1, v3
	v_cndmask_b32_e32 v0, v0, v5, vcc
	v_sub_u32_e32 v5, v4, v2
	v_cndmask_b32_e32 v4, v4, v5, vcc
	v_cmp_ge_u32_e32 vcc, v4, v2
	v_add_u32_e32 v4, 1, v0
	s_nop 0
	v_cndmask_b32_e32 v0, v0, v4, vcc
	v_mul_lo_u32 v4, v2, v0
	v_add_u32_e32 v2, v4, v2
	v_cmp_ne_u32_e32 vcc, v3, v2
	v_mov_b64_e32 v[2:3], s[2:3]
	s_mov_b32 s16, 0
	s_and_saveexec_b64 s[2:3], vcc
	s_cbranch_execz .LBB0_600
	s_mov_b32 s16, 1
	v_readlane_b32 s4, v215, 26
	v_readlane_b32 s5, v215, 27
	s_mov_b64 s[6:7], 0
	s_nop 3
	global_load_dword v2, v1, s[4:5] sc1
	s_waitcnt vmcnt(0)
	v_cmp_eq_u32_e32 vcc, v2, v0
	s_and_saveexec_b64 s[4:5], vcc
	s_cbranch_execz .LBB0_599
	s_mov_b32 s16, 1
	s_branch .LBB0_592
